# v21 = v15 + ResAdd and EpiStore epilogue row-sum reductions via v_permlane16/32_swap instead of ds_bpermute round trips
# baseline (speedup 1.0000x reference)
;     __device__ __forceinline__ void operator()(const f32x4 (&acc)[2][2][4][2], const Unit& u, int wr, int wc, int fr, int fq) const {
;     ...
;         if (!colmode) {
;             f32x4 pq[2][4];
; #pragma unroll
;             for (int ai = 0; ai < 2; ++ai)
; #pragma unroll
;                 for (int m = 0; m < 4; ++m) pq[ai][m] = *(const f32x4*)(ssq + (size_t)(row0 + ai * HALF + m * 16) * 16 + 4 * fq);
; #pragma unroll
;             for (int ai = 0; ai < 2; ++ai)
; #pragma unroll
;                 for (int m = 0; m < 4; ++m) { float s = (pq[ai][m][0] + pq[ai][m][1]) + (pq[ai][m][2] + pq[ai][m][3]); s += __shfl_xor(s, 16); s += __shfl_xor(s, 32); rsv[ai][m] = __builtin_amdgcn_rsqf(s * (1.0f / 1024.0f) + 1e-6f); }
.LBB0_376:
	v_mov_b32_e32 v194, 1.0
	s_andn2_b64 vcc, exec, s[0:1]
	v_mov_b32_e32 v192, 1.0
	v_mov_b32_e32 v190, 1.0
	v_mov_b32_e32 v188, 1.0
	v_mov_b32_e32 v142, 1.0
	v_mov_b32_e32 v138, 1.0
	v_mov_b32_e32 v136, 1.0
	v_mov_b32_e32 v134, 1.0
	s_cbranch_vccnz .LBB0_378
	v_ashrrev_i32_e32 v169, 31, v168
	v_lshlrev_b64 v[130:131], 6, v[168:169]
	v_lshl_add_u64 v[130:131], v[160:161], 0, v[130:131]
	global_load_dwordx4 v[170:173], v[130:131], off
	v_or_b32_e32 v186, 16, v168
	v_ashrrev_i32_e32 v187, 31, v186
	v_lshlrev_b64 v[130:131], 6, v[186:187]
	v_lshl_add_u64 v[130:131], v[160:161], 0, v[130:131]
	global_load_dwordx4 v[174:177], v[130:131], off
	v_or_b32_e32 v184, 32, v168
	v_ashrrev_i32_e32 v185, 31, v184
	v_lshlrev_b64 v[130:131], 6, v[184:185]
	v_lshl_add_u64 v[130:131], v[160:161], 0, v[130:131]
	global_load_dwordx4 v[178:181], v[130:131], off
	v_or_b32_e32 v182, 48, v168
	v_ashrrev_i32_e32 v183, 31, v182
	v_lshlrev_b64 v[130:131], 6, v[182:183]
	v_lshl_add_u64 v[130:131], v[160:161], 0, v[130:131]
	global_load_dwordx4 v[196:199], v[130:131], off
	v_add_u32_e32 v152, 0x80, v168
	v_ashrrev_i32_e32 v153, 31, v152
	v_lshlrev_b64 v[130:131], 6, v[152:153]
	v_add_u32_e32 v150, 0x90, v168
	v_lshl_add_u64 v[130:131], v[160:161], 0, v[130:131]
	v_ashrrev_i32_e32 v151, 31, v150
	global_load_dwordx4 v[142:145], v[130:131], off
	v_lshlrev_b64 v[130:131], 6, v[150:151]
	v_add_u32_e32 v148, 0xa0, v168
	v_lshl_add_u64 v[130:131], v[160:161], 0, v[130:131]
	v_ashrrev_i32_e32 v149, 31, v148
	global_load_dwordx4 v[138:141], v[130:131], off
	v_lshlrev_b64 v[130:131], 6, v[148:149]
	v_lshl_add_u64 v[130:131], v[160:161], 0, v[130:131]
	global_load_dwordx4 v[134:137], v[130:131], off
	v_add_u32_e32 v146, 0xb0, v168
	v_ashrrev_i32_e32 v147, 31, v146
	v_lshlrev_b64 v[130:131], 6, v[146:147]
	v_and_b32_e32 v190, 64, v242
	v_lshl_add_u64 v[130:131], v[160:161], 0, v[130:131]
	v_xor_b32_e32 v188, 16, v242
	v_add_u32_e32 v190, 64, v190
	global_load_dwordx4 v[130:133], v[130:131], off
	v_cmp_lt_i32_e32 vcc, v188, v190
	s_waitcnt vmcnt(0)
	v_mov_b32_e32 v200, v171
	v_mov_b32_e32 v201, v172
	v_mov_b32_e32 v171, v173
	v_cndmask_b32_e32 v188, v242, v188, vcc
	v_pk_add_f32 v[170:171], v[200:201], v[170:171]
	v_lshlrev_b32_e32 v205, 2, v188
	v_add_f32_e32 v170, v170, v171
	v_mov_b32_e32 v171, v170
	s_nop 1
	v_permlane16_swap_b32_e32 v171, v170
	v_xor_b32_e32 v188, 32, v242
	v_cmp_lt_i32_e32 vcc, v188, v190
	s_waitcnt lgkmcnt(0)
	v_add_f32_e32 v170, v170, v171
	v_cndmask_b32_e32 v188, v242, v188, vcc
	v_lshlrev_b32_e32 v206, 2, v188
	v_mov_b32_e32 v171, v170
	s_nop 1
	v_permlane32_swap_b32_e32 v171, v170
	s_waitcnt lgkmcnt(0)
	v_add_f32_e32 v170, v170, v171
	v_fmamk_f32 v170, v170, 0x3a800000, v240
	v_rsq_f32_e32 v194, v170
	v_mov_b32_e32 v170, v175
	v_mov_b32_e32 v171, v176
	v_mov_b32_e32 v175, v177
	v_pk_add_f32 v[170:171], v[170:171], v[174:175]
	s_nop 0
	v_add_f32_e32 v170, v170, v171
	v_mov_b32_e32 v171, v170
	s_nop 1
	v_permlane16_swap_b32_e32 v171, v170
	s_waitcnt lgkmcnt(0)
	v_add_f32_e32 v170, v170, v171
	v_mov_b32_e32 v171, v170
	s_nop 1
	v_permlane32_swap_b32_e32 v171, v170
	s_waitcnt lgkmcnt(0)
	v_add_f32_e32 v170, v170, v171
	v_fmamk_f32 v170, v170, 0x3a800000, v240
	v_rsq_f32_e32 v192, v170
	v_mov_b32_e32 v170, v179
	v_mov_b32_e32 v171, v180
	v_mov_b32_e32 v179, v181
	v_pk_add_f32 v[170:171], v[170:171], v[178:179]
	s_nop 0
	v_add_f32_e32 v170, v170, v171
	v_mov_b32_e32 v171, v170
	s_nop 1
	v_permlane16_swap_b32_e32 v171, v170
	s_waitcnt lgkmcnt(0)
	v_add_f32_e32 v170, v170, v171
	v_mov_b32_e32 v171, v170
	s_nop 1
	v_permlane32_swap_b32_e32 v171, v170
	s_waitcnt lgkmcnt(0)
	v_add_f32_e32 v170, v170, v171
	v_fmamk_f32 v170, v170, 0x3a800000, v240
	v_rsq_f32_e32 v190, v170
	v_mov_b32_e32 v170, v197
	v_mov_b32_e32 v171, v198
	v_mov_b32_e32 v197, v199
	v_pk_add_f32 v[170:171], v[170:171], v[196:197]
	s_nop 0
	v_add_f32_e32 v170, v170, v171
	v_mov_b32_e32 v171, v170
	s_nop 1
	v_permlane16_swap_b32_e32 v171, v170
	s_waitcnt lgkmcnt(0)
	v_add_f32_e32 v170, v170, v171
	v_mov_b32_e32 v171, v170
	s_nop 1
	v_permlane32_swap_b32_e32 v171, v170
	s_waitcnt lgkmcnt(0)
	v_add_f32_e32 v170, v170, v171
	v_fmamk_f32 v170, v170, 0x3a800000, v240
	v_rsq_f32_e32 v188, v170
	v_mov_b32_e32 v170, v143
	v_mov_b32_e32 v171, v144
	v_mov_b32_e32 v143, v145
	v_mov_b32_e32 v144, v139
	v_mov_b32_e32 v145, v140
	v_mov_b32_e32 v139, v141
	v_mov_b32_e32 v140, v135
	v_mov_b32_e32 v141, v136
	v_mov_b32_e32 v135, v137
	v_pk_add_f32 v[134:135], v[140:141], v[134:135]
	v_pk_add_f32 v[142:143], v[170:171], v[142:143]
	v_add_f32_e32 v134, v134, v135
	v_mov_b32_e32 v135, v134
	s_nop 1
	v_permlane16_swap_b32_e32 v135, v134
	v_pk_add_f32 v[138:139], v[144:145], v[138:139]
	v_add_f32_e32 v142, v142, v143
	v_add_f32_e32 v138, v138, v139
	v_mov_b32_e32 v143, v142
	s_nop 1
	v_permlane16_swap_b32_e32 v143, v142
	s_waitcnt lgkmcnt(1)
	v_add_f32_e32 v134, v134, v135
	v_mov_b32_e32 v135, v134
	s_nop 1
	v_permlane32_swap_b32_e32 v135, v134
	v_mov_b32_e32 v139, v138
	s_nop 1
	v_permlane16_swap_b32_e32 v139, v138
	s_waitcnt lgkmcnt(2)
	v_add_f32_e32 v142, v142, v143
	v_mov_b32_e32 v143, v142
	s_nop 1
	v_permlane32_swap_b32_e32 v143, v142
	s_waitcnt lgkmcnt(2)
	v_add_f32_e32 v134, v134, v135
	v_fmamk_f32 v134, v134, 0x3a800000, v240
	v_rsq_f32_e32 v136, v134
	v_mov_b32_e32 v134, v131
	v_mov_b32_e32 v135, v132
	v_mov_b32_e32 v131, v133
	v_pk_add_f32 v[130:131], v[134:135], v[130:131]
	s_waitcnt lgkmcnt(1)
	v_add_f32_e32 v138, v138, v139
	v_add_f32_e32 v130, v130, v131
	v_mov_b32_e32 v131, v130
	s_nop 1
	v_permlane16_swap_b32_e32 v131, v130
	v_mov_b32_e32 v139, v138
	s_nop 1
	v_permlane32_swap_b32_e32 v139, v138
	s_waitcnt lgkmcnt(2)
	v_add_f32_e32 v142, v142, v143
	v_fmamk_f32 v142, v142, 0x3a800000, v240
	v_rsq_f32_e32 v142, v142
	s_waitcnt lgkmcnt(1)
	v_add_f32_e32 v130, v130, v131
	v_mov_b32_e32 v131, v130
	s_nop 1
	v_permlane32_swap_b32_e32 v131, v130
	s_waitcnt lgkmcnt(1)
	v_add_f32_e32 v138, v138, v139
	v_fmamk_f32 v138, v138, 0x3a800000, v240
	v_rsq_f32_e32 v138, v138
	s_waitcnt lgkmcnt(0)
	v_add_f32_e32 v130, v130, v131
	v_fmamk_f32 v130, v130, 0x3a800000, v240
	v_rsq_f32_e32 v134, v130
	v_mov_b32_e32 v130, 1.0
	v_mov_b32_e32 v131, v130
	v_mov_b32_e32 v132, v130
	v_mov_b32_e32 v133, v130
	v_mov_b32_e32 v178, v130
	v_mov_b32_e32 v179, v130
	v_mov_b32_e32 v180, v130
	v_mov_b32_e32 v181, v130
	v_mov_b32_e32 v174, v130
	v_mov_b32_e32 v175, v130
	v_mov_b32_e32 v176, v130
	v_mov_b32_e32 v177, v130
	v_mov_b32_e32 v170, v130
	v_mov_b32_e32 v171, v130
	v_mov_b32_e32 v172, v130
	v_mov_b32_e32 v173, v130

; __device__ __forceinline__ unsigned cvt_pk_bf16(float lo, float hi) { unsigned r; asm volatile("v_cvt_pk_bf16_f32 %0, %1, %2" : "=v"(r) : "v"(lo), "v"(hi)); return r; }
;     __device__ __forceinline__ void operator()(const f32x4 (&acc)[2][2][4][2], const Unit& u, int wr, int wc, int fr, int fq) const {
;         const int row0 = u.pm * BM + wr * 64 + fr, col0 = u.pn * BM + wc * 32 + 8 * fq;
;         const unsigned lane_off = (unsigned)(fr * ldx + 8 * fq) * 2u;
;         const char* ub = (const char*)XB + ((size_t)(u.pm * BM + wr * 64) * ldx + u.pn * BM + wc * 32) * 2;
;         u32x4 ow[2][4][2];
; #pragma unroll
;         for (int ai = 0; ai < 2; ++ai)
; #pragma unroll
;             for (int m = 0; m < 4; ++m)
; #pragma unroll
;                 for (int bj = 0; bj < 2; ++bj) ow[ai][m][bj] = *(const u32x4*)(ub + ((size_t)(ai * HALF + m * 16) * ldx + bj * HALF) * 2 + lane_off);
; #pragma unroll
;         for (int ai = 0; ai < 2; ++ai)
; #pragma unroll
;             for (int m = 0; m < 4; ++m) {
;                 char* bp = (char*)ub + (size_t)(ai * HALF + m * 16) * ldx * 2;
;                 float sq = 0.f;
; #pragma unroll
;                 for (int bj = 0; bj < 2; ++bj) {
;                     const u32x4 w0 = ow[ai][m][bj];
;                     const f32x4 a0 = acc[ai][bj][m][0] * scale, a1 = acc[ai][bj][m][1] * scale;
;                     float o[8];
;                     o[0] = __uint_as_float(w0.x << 16) + a0[0]; o[1] = __uint_as_float(w0.x & 0xffff0000u) + a0[1]; o[2] = __uint_as_float(w0.y << 16) + a0[2]; o[3] = __uint_as_float(w0.y & 0xffff0000u) + a0[3];
;                     o[4] = __uint_as_float(w0.z << 16) + a1[0]; o[5] = __uint_as_float(w0.z & 0xffff0000u) + a1[1]; o[6] = __uint_as_float(w0.w << 16) + a1[2]; o[7] = __uint_as_float(w0.w & 0xffff0000u) + a1[3];
;                     sq += ((o[0] * o[0] + o[1] * o[1]) + (o[2] * o[2] + o[3] * o[3])) + ((o[4] * o[4] + o[5] * o[5]) + (o[6] * o[6] + o[7] * o[7]));
;                     u32x4 w; w.x = cvt_pk_bf16(o[0], o[1]); w.y = cvt_pk_bf16(o[2], o[3]); w.z = cvt_pk_bf16(o[4], o[5]); w.w = cvt_pk_bf16(o[6], o[7]);
;                     *(u32x4*)(bp + bj * HALF * 2 + lane_off) = w;
;                 }
;                 sq += __shfl_xor(sq, 16); sq += __shfl_xor(sq, 32);
;                 if (fq == 0) ssq[(size_t)(row0 + ai * HALF + m * 16) * 16 + u.pn * 4 + wc] = sq;
.LBB0_422:
	s_lshl_b32 s24, s62, 8
	s_lshl_b32 s44, s20, 8
	s_add_i32 s24, s24, s57
	s_ashr_i32 s45, s44, 31
	s_ashr_i32 s25, s24, 31
	s_or_b64 s[44:45], s[44:45], s[18:19]
	s_lshl_b64 s[62:63], s[24:25], 11
	s_lshl_b64 s[44:45], s[44:45], 1
	s_add_u32 s25, s48, s62
	s_addc_u32 s62, s49, s63
	s_add_u32 s44, s25, s44
	s_addc_u32 s45, s62, s45
	v_lshl_add_u64 v[206:207], s[44:45], 0, v[194:195]
	global_load_dwordx4 v[178:181], v[206:207], off
	global_load_dwordx4 v[182:185], v[206:207], off offset:256
	s_lshl_b32 s44, s20, 2
	s_mov_b32 s20, 0x8000
	v_pk_mul_f32 v[214:215], v[196:197], v[114:115]
	v_add_co_u32_e32 v114, vcc, s20, v206
	v_mov_b32_e32 v193, v192
	s_nop 0
	v_addc_co_u32_e32 v115, vcc, 0, v207, vcc
	s_mov_b32 s20, 0x10000
	v_pk_mul_f32 v[218:219], v[192:193], v[116:117]
	v_add_co_u32_e32 v116, vcc, s20, v206
	s_mov_b32 s20, 0x18000
	s_nop 0
	v_addc_co_u32_e32 v117, vcc, 0, v207, vcc
	v_pk_mul_f32 v[212:213], v[196:197], v[118:119]
	v_add_co_u32_e32 v118, vcc, s20, v206
	s_mov_b32 s20, 0x40000
	s_nop 0
	v_addc_co_u32_e32 v119, vcc, 0, v207, vcc
	v_pk_mul_f32 v[216:217], v[192:193], v[120:121]
	v_add_co_u32_e32 v120, vcc, s20, v206
	s_mov_b32 s20, 0x48000
	s_nop 0
	v_addc_co_u32_e32 v121, vcc, 0, v207, vcc
	v_add_co_u32_e32 v130, vcc, s20, v206
	s_mov_b32 s20, 0x50000
	s_nop 0
	v_addc_co_u32_e32 v131, vcc, 0, v207, vcc
	v_add_co_u32_e32 v132, vcc, s20, v206
	s_mov_b32 s20, 0x58000
	s_nop 0
	v_addc_co_u32_e32 v133, vcc, 0, v207, vcc
	v_add_co_u32_e32 v220, vcc, s20, v206
	v_pk_mul_f32 v[126:127], v[196:197], v[126:127]
	s_nop 0
	v_addc_co_u32_e32 v221, vcc, 0, v207, vcc
	global_load_dwordx4 v[174:177], v[114:115], off
	global_load_dwordx4 v[170:173], v[114:115], off offset:256
	global_load_dwordx4 v[166:169], v[116:117], off
	global_load_dwordx4 v[162:165], v[116:117], off offset:256
	global_load_dwordx4 v[158:161], v[118:119], off
	global_load_dwordx4 v[154:157], v[118:119], off offset:256
	global_load_dwordx4 v[150:153], v[120:121], off
	global_load_dwordx4 v[146:149], v[120:121], off offset:256
	global_load_dwordx4 v[142:145], v[130:131], off
	global_load_dwordx4 v[138:141], v[130:131], off offset:256
	global_load_dwordx4 v[134:137], v[132:133], off
	s_nop 0
	global_load_dwordx4 v[130:133], v[132:133], off offset:256
	s_nop 0
	global_load_dwordx4 v[118:121], v[220:221], off
	global_load_dwordx4 v[114:117], v[220:221], off offset:256
	v_pk_mul_f32 v[128:129], v[192:193], v[128:129]
	v_pk_mul_f32 v[122:123], v[196:197], v[122:123]
	v_pk_mul_f32 v[124:125], v[192:193], v[124:125]
	v_or_b32_e32 v208, s24, v205
	s_ashr_i32 s45, s44, 31
	s_waitcnt vmcnt(0)
	v_lshlrev_b32_e32 v209, 16, v178
	v_and_b32_e32 v178, 0xffff0000, v178
	v_lshlrev_b32_e32 v220, 16, v179
	v_and_b32_e32 v179, 0xffff0000, v179
	v_lshlrev_b32_e32 v221, 16, v180
	v_and_b32_e32 v180, 0xffff0000, v180
	v_lshlrev_b32_e32 v222, 16, v181
	v_and_b32_e32 v181, 0xffff0000, v181
	v_add_f32_e32 v178, v213, v178
	v_add_f32_e32 v179, v217, v179
	v_add_f32_e32 v180, v215, v180
	v_add_f32_e32 v181, v219, v181
	v_add_f32_e32 v209, v212, v209
	v_add_f32_e32 v212, v216, v220
	v_add_f32_e32 v213, v214, v221
	v_add_f32_e32 v214, v218, v222
	v_mul_f32_e32 v215, v178, v178
	v_mul_f32_e32 v216, v179, v179
	v_mul_f32_e32 v217, v180, v180
	v_mul_f32_e32 v218, v181, v181
	v_fmac_f32_e32 v215, v209, v209
	v_fmac_f32_e32 v216, v212, v212
	v_fmac_f32_e32 v217, v213, v213
	v_fmac_f32_e32 v218, v214, v214
	v_cvt_pk_bf16_f32 v178, v209, v178
	v_cvt_pk_bf16_f32 v179, v212, v179
	v_add_f32_e32 v209, v215, v216
	v_add_f32_e32 v212, v217, v218
	v_add_f32_e32 v209, v209, v212
	v_lshlrev_b32_e32 v212, 16, v182
	v_and_b32_e32 v182, 0xffff0000, v182
	v_add_f32_e32 v127, v127, v182
	v_lshlrev_b32_e32 v182, 16, v183
	v_add_f32_e32 v128, v128, v182
	v_and_b32_e32 v182, 0xffff0000, v183
	v_add_f32_e32 v129, v129, v182
	v_lshlrev_b32_e32 v182, 16, v184
	v_add_f32_e32 v182, v122, v182
	v_and_b32_e32 v122, 0xffff0000, v184
	v_add_f32_e32 v183, v123, v122
	v_lshlrev_b32_e32 v122, 16, v185
	v_add_f32_e32 v184, v124, v122
	v_and_b32_e32 v122, 0xffff0000, v185
	v_add_f32_e32 v126, v126, v212
	v_add_f32_e32 v185, v125, v122
	v_mul_f32_e32 v122, v127, v127
	v_mul_f32_e32 v123, v129, v129
	v_fmac_f32_e32 v122, v126, v126
	v_fmac_f32_e32 v123, v128, v128
	v_add_f32_e32 v122, v122, v123
	v_mul_f32_e32 v123, v183, v183
	v_mul_f32_e32 v124, v185, v185
	v_fmac_f32_e32 v123, v182, v182
	v_fmac_f32_e32 v124, v184, v184
	v_add_f32_e32 v123, v123, v124
	v_add_f32_e32 v122, v122, v123
	v_and_b32_e32 v124, 64, v242
	v_add_f32_e32 v123, v209, v122
	v_xor_b32_e32 v122, 16, v242
	v_add_u32_e32 v125, 64, v124
	v_cmp_lt_i32_e32 vcc, v122, v125
	v_ashrrev_i32_e32 v209, 31, v208
	v_cvt_pk_bf16_f32 v180, v213, v180
	v_cvt_pk_bf16_f32 v181, v214, v181
	global_store_dwordx4 v[206:207], v[178:181], off
	v_cndmask_b32_e32 v122, v242, v122, vcc
	v_lshlrev_b32_e32 v122, 2, v122
	v_mov_b32_e32 v124, v123
	s_nop 1
	v_permlane16_swap_b32_e32 v124, v123
	v_cvt_pk_bf16_f32 v126, v126, v127
	v_cvt_pk_bf16_f32 v127, v128, v129
	v_cvt_pk_bf16_f32 v128, v182, v183
	v_cvt_pk_bf16_f32 v129, v184, v185
	s_waitcnt lgkmcnt(0)
	v_add_f32_e32 v124, v123, v124
	v_xor_b32_e32 v123, 32, v242
	v_cmp_lt_i32_e32 vcc, v123, v125
	global_store_dwordx4 v[206:207], v[126:129], off offset:256
	s_nop 0
	v_cndmask_b32_e32 v123, v242, v123, vcc
	v_lshlrev_b32_e32 v123, 2, v123
	v_mov_b32_e32 v125, v124
	s_nop 1
	v_permlane32_swap_b32_e32 v125, v124
	s_and_saveexec_b64 s[24:25], s[4:5]
	s_cbranch_execz .LBB0_424
	v_lshlrev_b64 v[126:127], 6, v[208:209]
	v_lshl_add_u64 v[126:127], s[12:13], 0, v[126:127]
	v_lshl_add_u64 v[126:127], s[44:45], 2, v[126:127]
	s_lshl_b32 s20, s55, 2
	v_lshl_add_u64 v[126:127], v[126:127], 0, s[20:21]
	s_waitcnt lgkmcnt(0)
	v_add_f32_e32 v124, v124, v125
	global_store_dword v[126:127], v124, off
; __device__ __forceinline__ unsigned cvt_pk_bf16(float lo, float hi) { unsigned r; asm volatile("v_cvt_pk_bf16_f32 %0, %1, %2" : "=v"(r) : "v"(lo), "v"(hi)); return r; }
;     __device__ __forceinline__ void operator()(const f32x4 (&acc)[2][2][4][2], const Unit& u, int wr, int wc, int fr, int fq) const {
;     ...
;         for (int ai = 0; ai < 2; ++ai)
; #pragma unroll
;             for (int m = 0; m < 4; ++m) {
;                 char* bp = (char*)ub + (size_t)(ai * HALF + m * 16) * ldx * 2;
;                 float sq = 0.f;
; #pragma unroll
;                 for (int bj = 0; bj < 2; ++bj) {
;                     const u32x4 w0 = ow[ai][m][bj];
;                     const f32x4 a0 = acc[ai][bj][m][0] * scale, a1 = acc[ai][bj][m][1] * scale;
;                     float o[8];
;                     o[0] = __uint_as_float(w0.x << 16) + a0[0]; o[1] = __uint_as_float(w0.x & 0xffff0000u) + a0[1]; o[2] = __uint_as_float(w0.y << 16) + a0[2]; o[3] = __uint_as_float(w0.y & 0xffff0000u) + a0[3];
;                     o[4] = __uint_as_float(w0.z << 16) + a1[0]; o[5] = __uint_as_float(w0.z & 0xffff0000u) + a1[1]; o[6] = __uint_as_float(w0.w << 16) + a1[2]; o[7] = __uint_as_float(w0.w & 0xffff0000u) + a1[3];
;                     sq += ((o[0] * o[0] + o[1] * o[1]) + (o[2] * o[2] + o[3] * o[3])) + ((o[4] * o[4] + o[5] * o[5]) + (o[6] * o[6] + o[7] * o[7]));
;                     u32x4 w; w.x = cvt_pk_bf16(o[0], o[1]); w.y = cvt_pk_bf16(o[2], o[3]); w.z = cvt_pk_bf16(o[4], o[5]); w.w = cvt_pk_bf16(o[6], o[7]);
;                     *(u32x4*)(bp + bj * HALF * 2 + lane_off) = w;
;                 }
;                 sq += __shfl_xor(sq, 16); sq += __shfl_xor(sq, 32);
;                 if (fq == 0) ssq[(size_t)(row0 + ai * HALF + m * 16) * 16 + u.pn * 4 + wc] = sq;
.LBB0_424:
	s_or_b64 exec, exec, s[24:25]
	v_pk_mul_f32 v[110:111], v[196:197], v[110:111]
	v_lshlrev_b32_e32 v128, 16, v174
	v_add_f32_e32 v110, v110, v128
	v_and_b32_e32 v128, 0xffff0000, v174
	v_pk_mul_f32 v[112:113], v[192:193], v[112:113]
	v_add_f32_e32 v111, v111, v128
	v_lshlrev_b32_e32 v128, 16, v175
	v_add_f32_e32 v112, v112, v128
	v_and_b32_e32 v128, 0xffff0000, v175
	v_pk_mul_f32 v[106:107], v[196:197], v[106:107]
	v_add_f32_e32 v113, v113, v128
	v_lshlrev_b32_e32 v128, 16, v176
	v_add_f32_e32 v128, v106, v128
	v_and_b32_e32 v106, 0xffff0000, v176
	v_pk_mul_f32 v[108:109], v[192:193], v[108:109]
	v_add_f32_e32 v129, v107, v106
	v_lshlrev_b32_e32 v106, 16, v177
	v_add_f32_e32 v174, v108, v106
	v_and_b32_e32 v106, 0xffff0000, v177
	v_add_f32_e32 v109, v109, v106
	v_mul_f32_e32 v106, v111, v111
	v_mul_f32_e32 v107, v113, v113
	v_fmac_f32_e32 v106, v110, v110
	v_fmac_f32_e32 v107, v112, v112
	v_add_f32_e32 v106, v106, v107
	v_mul_f32_e32 v107, v129, v129
	v_mul_f32_e32 v108, v109, v109
	v_fmac_f32_e32 v107, v128, v128
	v_fmac_f32_e32 v108, v174, v174
	v_add_f32_e32 v107, v107, v108
	v_add_f32_e32 v108, v106, v107
	v_cvt_pk_bf16_f32 v106, v110, v111
	v_pk_mul_f32 v[102:103], v[196:197], v[102:103]
	v_lshlrev_b32_e32 v110, 16, v170
	v_add_f32_e32 v102, v102, v110
	v_and_b32_e32 v110, 0xffff0000, v170
	v_pk_mul_f32 v[104:105], v[192:193], v[104:105]
	v_add_f32_e32 v103, v103, v110
	v_lshlrev_b32_e32 v110, 16, v171
	v_add_f32_e32 v104, v104, v110
	v_and_b32_e32 v110, 0xffff0000, v171
	v_pk_mul_f32 v[98:99], v[196:197], v[98:99]
	v_add_f32_e32 v105, v105, v110
	v_lshlrev_b32_e32 v110, 16, v172
	v_add_f32_e32 v110, v98, v110
	v_and_b32_e32 v98, 0xffff0000, v172
	v_pk_mul_f32 v[100:101], v[192:193], v[100:101]
	v_add_f32_e32 v111, v99, v98
	v_lshlrev_b32_e32 v98, 16, v173
	v_cvt_pk_bf16_f32 v107, v112, v113
	v_add_f32_e32 v112, v100, v98
	v_and_b32_e32 v98, 0xffff0000, v173
	v_add_f32_e32 v113, v101, v98
	v_mul_f32_e32 v98, v103, v103
	v_mul_f32_e32 v99, v105, v105
	v_fmac_f32_e32 v98, v102, v102
	v_fmac_f32_e32 v99, v104, v104
	v_add_f32_e32 v98, v98, v99
	v_mul_f32_e32 v99, v111, v111
	v_mul_f32_e32 v100, v113, v113
	v_fmac_f32_e32 v99, v110, v110
	v_fmac_f32_e32 v100, v112, v112
	v_add_f32_e32 v99, v99, v100
	v_add_f32_e32 v98, v98, v99
	v_add_f32_e32 v98, v108, v98
	v_mov_b32_e32 v99, v98
	s_nop 1
	v_permlane16_swap_b32_e32 v99, v98
	s_mov_b64 s[24:25], 0x8000
	s_waitcnt lgkmcnt(1)
	v_lshl_add_u64 v[124:125], v[206:207], 0, s[24:25]
	s_mov_b64 s[24:25], 0x8100
	v_lshl_add_u64 v[126:127], v[206:207], 0, s[24:25]
	s_waitcnt lgkmcnt(0)
	v_add_f32_e32 v98, v98, v99
	v_mov_b32_e32 v99, v98
	s_nop 1
	v_permlane32_swap_b32_e32 v99, v98
	v_cvt_pk_bf16_f32 v108, v128, v129
	v_cvt_pk_bf16_f32 v109, v174, v109
	global_store_dwordx4 v[124:125], v[106:109], off
	v_cvt_pk_bf16_f32 v100, v102, v103
	v_cvt_pk_bf16_f32 v101, v104, v105
	v_cvt_pk_bf16_f32 v102, v110, v111
	v_cvt_pk_bf16_f32 v103, v112, v113
	global_store_dwordx4 v[126:127], v[100:103], off
	s_and_saveexec_b64 s[24:25], s[4:5]
	s_cbranch_execz .LBB0_426
	s_waitcnt lgkmcnt(0)
	v_add_f32_e32 v100, v98, v99
	v_or_b32_e32 v98, 16, v208
	v_ashrrev_i32_e32 v99, 31, v98
	v_lshlrev_b64 v[98:99], 6, v[98:99]
	v_lshl_add_u64 v[98:99], s[12:13], 0, v[98:99]
	v_lshl_add_u64 v[98:99], s[44:45], 2, v[98:99]
	s_lshl_b32 s20, s55, 2
	v_lshl_add_u64 v[98:99], v[98:99], 0, s[20:21]
	global_store_dword v[98:99], v100, off
.LBB0_426:
	s_or_b64 exec, exec, s[24:25]
	v_pk_mul_f32 v[94:95], v[196:197], v[94:95]
	v_lshlrev_b32_e32 v102, 16, v166
	v_mov_b32_e32 v193, v192
	v_add_f32_e32 v94, v94, v102
	v_and_b32_e32 v102, 0xffff0000, v166
	v_pk_mul_f32 v[96:97], v[192:193], v[96:97]
	v_add_f32_e32 v95, v95, v102
	v_lshlrev_b32_e32 v102, 16, v167
	v_add_f32_e32 v96, v96, v102
	v_and_b32_e32 v102, 0xffff0000, v167
	v_pk_mul_f32 v[90:91], v[196:197], v[90:91]
	v_add_f32_e32 v97, v97, v102
	v_lshlrev_b32_e32 v102, 16, v168
	v_add_f32_e32 v102, v90, v102
	v_and_b32_e32 v90, 0xffff0000, v168
	v_pk_mul_f32 v[92:93], v[192:193], v[92:93]
	v_add_f32_e32 v103, v91, v90
	v_lshlrev_b32_e32 v90, 16, v169
	v_add_f32_e32 v104, v92, v90
	v_and_b32_e32 v90, 0xffff0000, v169
	v_add_f32_e32 v93, v93, v90
	v_mul_f32_e32 v90, v95, v95
	v_mul_f32_e32 v91, v97, v97
	v_fmac_f32_e32 v90, v94, v94
	v_fmac_f32_e32 v91, v96, v96
	v_add_f32_e32 v90, v90, v91
	v_mul_f32_e32 v91, v103, v103
	v_mul_f32_e32 v92, v93, v93
	v_fmac_f32_e32 v91, v102, v102
	v_fmac_f32_e32 v92, v104, v104
	v_add_f32_e32 v91, v91, v92
	v_add_f32_e32 v92, v90, v91
	v_cvt_pk_bf16_f32 v90, v94, v95
	v_pk_mul_f32 v[86:87], v[196:197], v[86:87]
	v_lshlrev_b32_e32 v94, 16, v162
	v_add_f32_e32 v86, v86, v94
	v_and_b32_e32 v94, 0xffff0000, v162
	v_pk_mul_f32 v[88:89], v[192:193], v[88:89]
	v_add_f32_e32 v87, v87, v94
	v_lshlrev_b32_e32 v94, 16, v163
	v_add_f32_e32 v88, v88, v94
	v_and_b32_e32 v94, 0xffff0000, v163
	v_pk_mul_f32 v[82:83], v[196:197], v[82:83]
	v_add_f32_e32 v89, v89, v94
	v_lshlrev_b32_e32 v94, 16, v164
	v_add_f32_e32 v94, v82, v94
	v_and_b32_e32 v82, 0xffff0000, v164
	v_pk_mul_f32 v[84:85], v[192:193], v[84:85]
	v_add_f32_e32 v95, v83, v82
	v_lshlrev_b32_e32 v82, 16, v165
	v_cvt_pk_bf16_f32 v91, v96, v97
	v_add_f32_e32 v96, v84, v82
	v_and_b32_e32 v82, 0xffff0000, v165
	v_add_f32_e32 v97, v85, v82
	v_mul_f32_e32 v82, v87, v87
	v_mul_f32_e32 v83, v89, v89
	v_fmac_f32_e32 v82, v86, v86
	v_fmac_f32_e32 v83, v88, v88
	v_add_f32_e32 v82, v82, v83
	v_mul_f32_e32 v83, v95, v95
	v_mul_f32_e32 v84, v97, v97
	v_fmac_f32_e32 v83, v94, v94
	v_fmac_f32_e32 v84, v96, v96
	v_add_f32_e32 v83, v83, v84
	v_add_f32_e32 v82, v82, v83
	v_add_f32_e32 v82, v92, v82
	v_mov_b32_e32 v83, v82
	s_nop 1
	v_permlane16_swap_b32_e32 v83, v82
	s_mov_b64 s[24:25], 0x10100
	s_waitcnt lgkmcnt(1)
	v_lshl_add_u64 v[98:99], v[206:207], 0, s[86:87]
	v_lshl_add_u64 v[100:101], v[206:207], 0, s[24:25]
	v_cvt_pk_bf16_f32 v92, v102, v103
	s_waitcnt lgkmcnt(0)
	v_add_f32_e32 v82, v82, v83
	v_mov_b32_e32 v83, v82
	s_nop 1
	v_permlane32_swap_b32_e32 v83, v82
	v_cvt_pk_bf16_f32 v93, v104, v93
	global_store_dwordx4 v[98:99], v[90:93], off
	v_cvt_pk_bf16_f32 v84, v86, v87
	v_cvt_pk_bf16_f32 v85, v88, v89
	v_cvt_pk_bf16_f32 v86, v94, v95
	v_cvt_pk_bf16_f32 v87, v96, v97
	global_store_dwordx4 v[100:101], v[84:87], off
	s_and_saveexec_b64 s[24:25], s[4:5]
	s_mov_b32 s68, 0xffff0000
	s_mov_b32 s69, -1
	s_cbranch_execz .LBB0_428
	s_waitcnt lgkmcnt(0)
	v_add_f32_e32 v84, v82, v83
	v_or_b32_e32 v82, 32, v208
	v_ashrrev_i32_e32 v83, 31, v82
	v_lshlrev_b64 v[82:83], 6, v[82:83]
	v_lshl_add_u64 v[82:83], s[12:13], 0, v[82:83]
	v_lshl_add_u64 v[82:83], s[44:45], 2, v[82:83]
	s_lshl_b32 s20, s55, 2
	v_lshl_add_u64 v[82:83], v[82:83], 0, s[20:21]
	global_store_dword v[82:83], v84, off
; __device__ __forceinline__ unsigned cvt_pk_bf16(float lo, float hi) { unsigned r; asm volatile("v_cvt_pk_bf16_f32 %0, %1, %2" : "=v"(r) : "v"(lo), "v"(hi)); return r; }
;     __device__ __forceinline__ void operator()(const f32x4 (&acc)[2][2][4][2], const Unit& u, int wr, int wc, int fr, int fq) const {
;     ...
;         for (int ai = 0; ai < 2; ++ai)
; #pragma unroll
;             for (int m = 0; m < 4; ++m) {
;                 char* bp = (char*)ub + (size_t)(ai * HALF + m * 16) * ldx * 2;
;                 float sq = 0.f;
; #pragma unroll
;                 for (int bj = 0; bj < 2; ++bj) {
;                     const u32x4 w0 = ow[ai][m][bj];
;                     const f32x4 a0 = acc[ai][bj][m][0] * scale, a1 = acc[ai][bj][m][1] * scale;
;                     float o[8];
;                     o[0] = __uint_as_float(w0.x << 16) + a0[0]; o[1] = __uint_as_float(w0.x & 0xffff0000u) + a0[1]; o[2] = __uint_as_float(w0.y << 16) + a0[2]; o[3] = __uint_as_float(w0.y & 0xffff0000u) + a0[3];
;                     o[4] = __uint_as_float(w0.z << 16) + a1[0]; o[5] = __uint_as_float(w0.z & 0xffff0000u) + a1[1]; o[6] = __uint_as_float(w0.w << 16) + a1[2]; o[7] = __uint_as_float(w0.w & 0xffff0000u) + a1[3];
;                     sq += ((o[0] * o[0] + o[1] * o[1]) + (o[2] * o[2] + o[3] * o[3])) + ((o[4] * o[4] + o[5] * o[5]) + (o[6] * o[6] + o[7] * o[7]));
;                     u32x4 w; w.x = cvt_pk_bf16(o[0], o[1]); w.y = cvt_pk_bf16(o[2], o[3]); w.z = cvt_pk_bf16(o[4], o[5]); w.w = cvt_pk_bf16(o[6], o[7]);
;                     *(u32x4*)(bp + bj * HALF * 2 + lane_off) = w;
;                 }
;                 sq += __shfl_xor(sq, 16); sq += __shfl_xor(sq, 32);
;                 if (fq == 0) ssq[(size_t)(row0 + ai * HALF + m * 16) * 16 + u.pn * 4 + wc] = sq;
.LBB0_428:
	s_or_b64 exec, exec, s[24:25]
	v_pk_mul_f32 v[78:79], v[196:197], v[78:79]
	v_lshlrev_b32_e32 v86, 16, v158
	v_add_f32_e32 v78, v78, v86
	v_and_b32_e32 v86, 0xffff0000, v158
	v_pk_mul_f32 v[80:81], v[192:193], v[80:81]
	v_add_f32_e32 v79, v79, v86
	v_lshlrev_b32_e32 v86, 16, v159
	v_add_f32_e32 v80, v80, v86
	v_and_b32_e32 v86, 0xffff0000, v159
	v_pk_mul_f32 v[74:75], v[196:197], v[74:75]
	v_add_f32_e32 v81, v81, v86
	v_lshlrev_b32_e32 v86, 16, v160
	v_add_f32_e32 v86, v74, v86
	v_and_b32_e32 v74, 0xffff0000, v160
	v_pk_mul_f32 v[76:77], v[192:193], v[76:77]
	v_add_f32_e32 v87, v75, v74
	v_lshlrev_b32_e32 v74, 16, v161
	v_add_f32_e32 v88, v76, v74
	v_and_b32_e32 v74, 0xffff0000, v161
	v_add_f32_e32 v77, v77, v74
	v_mul_f32_e32 v74, v79, v79
	v_mul_f32_e32 v75, v81, v81
	v_fmac_f32_e32 v74, v78, v78
	v_fmac_f32_e32 v75, v80, v80
	v_add_f32_e32 v74, v74, v75
	v_mul_f32_e32 v75, v87, v87
	v_mul_f32_e32 v76, v77, v77
	v_fmac_f32_e32 v75, v86, v86
	v_fmac_f32_e32 v76, v88, v88
	v_add_f32_e32 v75, v75, v76
	v_add_f32_e32 v76, v74, v75
	v_cvt_pk_bf16_f32 v74, v78, v79
	v_pk_mul_f32 v[70:71], v[196:197], v[70:71]
	v_lshlrev_b32_e32 v78, 16, v154
	v_add_f32_e32 v70, v70, v78
	v_and_b32_e32 v78, 0xffff0000, v154
	v_pk_mul_f32 v[72:73], v[192:193], v[72:73]
	v_add_f32_e32 v71, v71, v78
	v_lshlrev_b32_e32 v78, 16, v155
	v_add_f32_e32 v72, v72, v78
	v_and_b32_e32 v78, 0xffff0000, v155
	v_pk_mul_f32 v[66:67], v[196:197], v[66:67]
	v_add_f32_e32 v73, v73, v78
	v_lshlrev_b32_e32 v78, 16, v156
	v_add_f32_e32 v78, v66, v78
	v_and_b32_e32 v66, 0xffff0000, v156
	v_pk_mul_f32 v[68:69], v[192:193], v[68:69]
	v_add_f32_e32 v79, v67, v66
	v_lshlrev_b32_e32 v66, 16, v157
	v_cvt_pk_bf16_f32 v75, v80, v81
	v_add_f32_e32 v80, v68, v66
	v_and_b32_e32 v66, 0xffff0000, v157
	v_add_f32_e32 v81, v69, v66
	v_mul_f32_e32 v66, v71, v71
	v_mul_f32_e32 v67, v73, v73
	v_fmac_f32_e32 v66, v70, v70
	v_fmac_f32_e32 v67, v72, v72
	v_add_f32_e32 v66, v66, v67
	v_mul_f32_e32 v67, v79, v79
	v_mul_f32_e32 v68, v81, v81
	v_fmac_f32_e32 v67, v78, v78
	v_fmac_f32_e32 v68, v80, v80
	v_add_f32_e32 v67, v67, v68
	v_add_f32_e32 v66, v66, v67
	v_add_f32_e32 v66, v76, v66
	v_mov_b32_e32 v67, v66
	s_nop 1
	v_permlane16_swap_b32_e32 v67, v66
	s_mov_b64 s[24:25], 0x18000
	s_waitcnt lgkmcnt(1)
	v_lshl_add_u64 v[82:83], v[206:207], 0, s[24:25]
	s_mov_b64 s[24:25], 0x18100
	v_lshl_add_u64 v[84:85], v[206:207], 0, s[24:25]
	s_waitcnt lgkmcnt(0)
	v_add_f32_e32 v66, v66, v67
	v_mov_b32_e32 v67, v66
	s_nop 1
	v_permlane32_swap_b32_e32 v67, v66
	v_cvt_pk_bf16_f32 v76, v86, v87
	v_cvt_pk_bf16_f32 v77, v88, v77
	global_store_dwordx4 v[82:83], v[74:77], off
	v_cvt_pk_bf16_f32 v68, v70, v71
	v_cvt_pk_bf16_f32 v69, v72, v73
	v_cvt_pk_bf16_f32 v70, v78, v79
	v_cvt_pk_bf16_f32 v71, v80, v81
	global_store_dwordx4 v[84:85], v[68:71], off
	s_and_saveexec_b64 s[24:25], s[4:5]
	s_cbranch_execz .LBB0_430
	s_waitcnt lgkmcnt(0)
	v_add_f32_e32 v68, v66, v67
	v_or_b32_e32 v66, 48, v208
	v_ashrrev_i32_e32 v67, 31, v66
	v_lshlrev_b64 v[66:67], 6, v[66:67]
	v_lshl_add_u64 v[66:67], s[12:13], 0, v[66:67]
	v_lshl_add_u64 v[66:67], s[44:45], 2, v[66:67]
	s_lshl_b32 s20, s55, 2
	v_lshl_add_u64 v[66:67], v[66:67], 0, s[20:21]
	global_store_dword v[66:67], v68, off
.LBB0_430:
	s_or_b64 exec, exec, s[24:25]
	v_pk_mul_f32 v[62:63], v[196:197], v[62:63]
	v_lshlrev_b32_e32 v70, 16, v150
	v_mov_b32_e32 v193, v192
	v_add_f32_e32 v62, v62, v70
	v_and_b32_e32 v70, 0xffff0000, v150
	v_pk_mul_f32 v[64:65], v[192:193], v[64:65]
	v_add_f32_e32 v63, v63, v70
	v_lshlrev_b32_e32 v70, 16, v151
	v_add_f32_e32 v64, v64, v70
	v_and_b32_e32 v70, 0xffff0000, v151
	v_pk_mul_f32 v[58:59], v[196:197], v[58:59]
	v_add_f32_e32 v65, v65, v70
	v_lshlrev_b32_e32 v70, 16, v152
	v_add_f32_e32 v70, v58, v70
	v_and_b32_e32 v58, 0xffff0000, v152
	v_pk_mul_f32 v[60:61], v[192:193], v[60:61]
	v_add_f32_e32 v71, v59, v58
	v_lshlrev_b32_e32 v58, 16, v153
	v_add_f32_e32 v72, v60, v58
	v_and_b32_e32 v58, 0xffff0000, v153
	v_add_f32_e32 v61, v61, v58
	v_mul_f32_e32 v58, v63, v63
	v_mul_f32_e32 v59, v65, v65
	v_fmac_f32_e32 v58, v62, v62
	v_fmac_f32_e32 v59, v64, v64
	v_add_f32_e32 v58, v58, v59
	v_mul_f32_e32 v59, v71, v71
	v_mul_f32_e32 v60, v61, v61
	v_fmac_f32_e32 v59, v70, v70
	v_fmac_f32_e32 v60, v72, v72
	v_add_f32_e32 v59, v59, v60
	v_add_f32_e32 v60, v58, v59
	v_cvt_pk_bf16_f32 v58, v62, v63
	v_pk_mul_f32 v[54:55], v[196:197], v[54:55]
	v_lshlrev_b32_e32 v62, 16, v146
	v_add_f32_e32 v54, v54, v62
	v_and_b32_e32 v62, 0xffff0000, v146
	v_pk_mul_f32 v[56:57], v[192:193], v[56:57]
	v_add_f32_e32 v55, v55, v62
	v_lshlrev_b32_e32 v62, 16, v147
	v_add_f32_e32 v56, v56, v62
	v_and_b32_e32 v62, 0xffff0000, v147
	v_pk_mul_f32 v[50:51], v[196:197], v[50:51]
	v_add_f32_e32 v57, v57, v62
	v_lshlrev_b32_e32 v62, 16, v148
	v_add_f32_e32 v62, v50, v62
	v_and_b32_e32 v50, 0xffff0000, v148
	v_pk_mul_f32 v[52:53], v[192:193], v[52:53]
	v_add_f32_e32 v63, v51, v50
	v_lshlrev_b32_e32 v50, 16, v149
	v_cvt_pk_bf16_f32 v59, v64, v65
	v_add_f32_e32 v64, v52, v50
	v_and_b32_e32 v50, 0xffff0000, v149
	v_add_f32_e32 v65, v53, v50
	v_mul_f32_e32 v50, v55, v55
	v_mul_f32_e32 v51, v57, v57
	v_fmac_f32_e32 v50, v54, v54
	v_fmac_f32_e32 v51, v56, v56
	v_add_f32_e32 v50, v50, v51
	v_mul_f32_e32 v51, v63, v63
	v_mul_f32_e32 v52, v65, v65
	v_fmac_f32_e32 v51, v62, v62
	v_fmac_f32_e32 v52, v64, v64
	v_add_f32_e32 v51, v51, v52
	v_add_f32_e32 v50, v50, v51
	v_add_f32_e32 v50, v60, v50
	v_mov_b32_e32 v51, v50
	s_nop 1
	v_permlane16_swap_b32_e32 v51, v50
	s_mov_b64 s[24:25], 0x40100
	s_waitcnt lgkmcnt(1)
	v_lshl_add_u64 v[66:67], v[206:207], 0, s[36:37]
	v_lshl_add_u64 v[68:69], v[206:207], 0, s[24:25]
	v_cvt_pk_bf16_f32 v60, v70, v71
	s_waitcnt lgkmcnt(0)
	v_add_f32_e32 v50, v50, v51
	v_mov_b32_e32 v51, v50
	s_nop 1
	v_permlane32_swap_b32_e32 v51, v50
	v_cvt_pk_bf16_f32 v61, v72, v61
	global_store_dwordx4 v[66:67], v[58:61], off
	v_cvt_pk_bf16_f32 v52, v54, v55
	v_cvt_pk_bf16_f32 v53, v56, v57
	v_cvt_pk_bf16_f32 v54, v62, v63
	v_cvt_pk_bf16_f32 v55, v64, v65
	global_store_dwordx4 v[68:69], v[52:55], off
	s_and_saveexec_b64 s[24:25], s[4:5]
	s_cbranch_execz .LBB0_432
	s_waitcnt lgkmcnt(0)
	v_add_f32_e32 v52, v50, v51
	v_lshlrev_b64 v[50:51], 6, v[208:209]
	v_lshl_add_u64 v[50:51], s[12:13], 0, v[50:51]
	v_lshl_add_u64 v[50:51], s[44:45], 2, v[50:51]
	s_lshl_b32 s20, s55, 2
	v_lshl_add_u64 v[50:51], v[50:51], 0, s[20:21]
	v_add_co_u32_e32 v50, vcc, 0x2000, v50
	s_nop 1
	v_addc_co_u32_e32 v51, vcc, 0, v51, vcc
	global_store_dword v[50:51], v52, off
; __device__ __forceinline__ unsigned cvt_pk_bf16(float lo, float hi) { unsigned r; asm volatile("v_cvt_pk_bf16_f32 %0, %1, %2" : "=v"(r) : "v"(lo), "v"(hi)); return r; }
;     __device__ __forceinline__ void operator()(const f32x4 (&acc)[2][2][4][2], const Unit& u, int wr, int wc, int fr, int fq) const {
;     ...
;         for (int ai = 0; ai < 2; ++ai)
; #pragma unroll
;             for (int m = 0; m < 4; ++m) {
;                 char* bp = (char*)ub + (size_t)(ai * HALF + m * 16) * ldx * 2;
;                 float sq = 0.f;
; #pragma unroll
;                 for (int bj = 0; bj < 2; ++bj) {
;                     const u32x4 w0 = ow[ai][m][bj];
;                     const f32x4 a0 = acc[ai][bj][m][0] * scale, a1 = acc[ai][bj][m][1] * scale;
;                     float o[8];
;                     o[0] = __uint_as_float(w0.x << 16) + a0[0]; o[1] = __uint_as_float(w0.x & 0xffff0000u) + a0[1]; o[2] = __uint_as_float(w0.y << 16) + a0[2]; o[3] = __uint_as_float(w0.y & 0xffff0000u) + a0[3];
;                     o[4] = __uint_as_float(w0.z << 16) + a1[0]; o[5] = __uint_as_float(w0.z & 0xffff0000u) + a1[1]; o[6] = __uint_as_float(w0.w << 16) + a1[2]; o[7] = __uint_as_float(w0.w & 0xffff0000u) + a1[3];
;                     sq += ((o[0] * o[0] + o[1] * o[1]) + (o[2] * o[2] + o[3] * o[3])) + ((o[4] * o[4] + o[5] * o[5]) + (o[6] * o[6] + o[7] * o[7]));
;                     u32x4 w; w.x = cvt_pk_bf16(o[0], o[1]); w.y = cvt_pk_bf16(o[2], o[3]); w.z = cvt_pk_bf16(o[4], o[5]); w.w = cvt_pk_bf16(o[6], o[7]);
;                     *(u32x4*)(bp + bj * HALF * 2 + lane_off) = w;
;                 }
;                 sq += __shfl_xor(sq, 16); sq += __shfl_xor(sq, 32);
;                 if (fq == 0) ssq[(size_t)(row0 + ai * HALF + m * 16) * 16 + u.pn * 4 + wc] = sq;
.LBB0_432:
	s_or_b64 exec, exec, s[24:25]
	v_pk_mul_f32 v[46:47], v[196:197], v[46:47]
	v_lshlrev_b32_e32 v54, 16, v142
	v_add_f32_e32 v46, v46, v54
	v_and_b32_e32 v54, 0xffff0000, v142
	v_pk_mul_f32 v[48:49], v[192:193], v[48:49]
	v_add_f32_e32 v47, v47, v54
	v_lshlrev_b32_e32 v54, 16, v143
	v_add_f32_e32 v48, v48, v54
	v_and_b32_e32 v54, 0xffff0000, v143
	v_pk_mul_f32 v[42:43], v[196:197], v[42:43]
	v_add_f32_e32 v49, v49, v54
	v_lshlrev_b32_e32 v54, 16, v144
	v_add_f32_e32 v54, v42, v54
	v_and_b32_e32 v42, 0xffff0000, v144
	v_pk_mul_f32 v[44:45], v[192:193], v[44:45]
	v_add_f32_e32 v55, v43, v42
	v_lshlrev_b32_e32 v42, 16, v145
	v_add_f32_e32 v56, v44, v42
	v_and_b32_e32 v42, 0xffff0000, v145
	v_add_f32_e32 v45, v45, v42
	v_mul_f32_e32 v42, v47, v47
	v_mul_f32_e32 v43, v49, v49
	v_fmac_f32_e32 v42, v46, v46
	v_fmac_f32_e32 v43, v48, v48
	v_add_f32_e32 v42, v42, v43
	v_mul_f32_e32 v43, v55, v55
	v_mul_f32_e32 v44, v45, v45
	v_fmac_f32_e32 v43, v54, v54
	v_fmac_f32_e32 v44, v56, v56
	v_add_f32_e32 v43, v43, v44
	v_add_f32_e32 v44, v42, v43
	v_cvt_pk_bf16_f32 v42, v46, v47
	v_pk_mul_f32 v[38:39], v[196:197], v[38:39]
	v_lshlrev_b32_e32 v46, 16, v138
	v_add_f32_e32 v38, v38, v46
	v_and_b32_e32 v46, 0xffff0000, v138
	v_pk_mul_f32 v[40:41], v[192:193], v[40:41]
	v_add_f32_e32 v39, v39, v46
	v_lshlrev_b32_e32 v46, 16, v139
	v_add_f32_e32 v40, v40, v46
	v_and_b32_e32 v46, 0xffff0000, v139
	v_pk_mul_f32 v[34:35], v[196:197], v[34:35]
	v_add_f32_e32 v41, v41, v46
	v_lshlrev_b32_e32 v46, 16, v140
	v_add_f32_e32 v46, v34, v46
	v_and_b32_e32 v34, 0xffff0000, v140
	v_pk_mul_f32 v[36:37], v[192:193], v[36:37]
	v_add_f32_e32 v47, v35, v34
	v_lshlrev_b32_e32 v34, 16, v141
	v_cvt_pk_bf16_f32 v43, v48, v49
	v_add_f32_e32 v48, v36, v34
	v_and_b32_e32 v34, 0xffff0000, v141
	v_add_f32_e32 v49, v37, v34
	v_mul_f32_e32 v34, v39, v39
	v_mul_f32_e32 v35, v41, v41
	v_fmac_f32_e32 v34, v38, v38
	v_fmac_f32_e32 v35, v40, v40
	v_add_f32_e32 v34, v34, v35
	v_mul_f32_e32 v35, v47, v47
	v_mul_f32_e32 v36, v49, v49
	v_fmac_f32_e32 v35, v46, v46
	v_fmac_f32_e32 v36, v48, v48
	v_add_f32_e32 v35, v35, v36
	v_add_f32_e32 v34, v34, v35
	v_add_f32_e32 v34, v44, v34
	v_mov_b32_e32 v35, v34
	s_nop 1
	v_permlane16_swap_b32_e32 v35, v34
	s_mov_b64 s[24:25], 0x48000
	s_waitcnt lgkmcnt(1)
	v_lshl_add_u64 v[50:51], v[206:207], 0, s[24:25]
	s_mov_b64 s[24:25], 0x48100
	v_lshl_add_u64 v[52:53], v[206:207], 0, s[24:25]
	s_waitcnt lgkmcnt(0)
	v_add_f32_e32 v34, v34, v35
	v_mov_b32_e32 v35, v34
	s_nop 1
	v_permlane32_swap_b32_e32 v35, v34
	v_cvt_pk_bf16_f32 v44, v54, v55
	v_cvt_pk_bf16_f32 v45, v56, v45
	global_store_dwordx4 v[50:51], v[42:45], off
	v_cvt_pk_bf16_f32 v36, v38, v39
	v_cvt_pk_bf16_f32 v37, v40, v41
	v_cvt_pk_bf16_f32 v38, v46, v47
	v_cvt_pk_bf16_f32 v39, v48, v49
	global_store_dwordx4 v[52:53], v[36:39], off
	s_and_saveexec_b64 s[24:25], s[4:5]
	s_cbranch_execz .LBB0_434
	s_waitcnt lgkmcnt(0)
	v_add_f32_e32 v36, v34, v35
	v_lshlrev_b64 v[34:35], 6, v[208:209]
	v_lshl_add_u64 v[34:35], s[12:13], 0, v[34:35]
	v_lshl_add_u64 v[34:35], s[44:45], 2, v[34:35]
	s_lshl_b32 s20, s55, 2
	v_lshl_add_u64 v[34:35], v[34:35], 0, s[20:21]
	v_add_co_u32_e32 v34, vcc, 0x2000, v34
	s_nop 1
	v_addc_co_u32_e32 v35, vcc, 0, v35, vcc
	global_store_dword v[34:35], v36, off offset:1024
; __device__ __forceinline__ unsigned cvt_pk_bf16(float lo, float hi) { unsigned r; asm volatile("v_cvt_pk_bf16_f32 %0, %1, %2" : "=v"(r) : "v"(lo), "v"(hi)); return r; }
;     __device__ __forceinline__ void operator()(const f32x4 (&acc)[2][2][4][2], const Unit& u, int wr, int wc, int fr, int fq) const {
;     ...
;         for (int ai = 0; ai < 2; ++ai)
; #pragma unroll
;             for (int m = 0; m < 4; ++m) {
;                 char* bp = (char*)ub + (size_t)(ai * HALF + m * 16) * ldx * 2;
;                 float sq = 0.f;
; #pragma unroll
;                 for (int bj = 0; bj < 2; ++bj) {
;                     const u32x4 w0 = ow[ai][m][bj];
;                     const f32x4 a0 = acc[ai][bj][m][0] * scale, a1 = acc[ai][bj][m][1] * scale;
;                     float o[8];
;                     o[0] = __uint_as_float(w0.x << 16) + a0[0]; o[1] = __uint_as_float(w0.x & 0xffff0000u) + a0[1]; o[2] = __uint_as_float(w0.y << 16) + a0[2]; o[3] = __uint_as_float(w0.y & 0xffff0000u) + a0[3];
;                     o[4] = __uint_as_float(w0.z << 16) + a1[0]; o[5] = __uint_as_float(w0.z & 0xffff0000u) + a1[1]; o[6] = __uint_as_float(w0.w << 16) + a1[2]; o[7] = __uint_as_float(w0.w & 0xffff0000u) + a1[3];
;                     sq += ((o[0] * o[0] + o[1] * o[1]) + (o[2] * o[2] + o[3] * o[3])) + ((o[4] * o[4] + o[5] * o[5]) + (o[6] * o[6] + o[7] * o[7]));
;                     u32x4 w; w.x = cvt_pk_bf16(o[0], o[1]); w.y = cvt_pk_bf16(o[2], o[3]); w.z = cvt_pk_bf16(o[4], o[5]); w.w = cvt_pk_bf16(o[6], o[7]);
;                     *(u32x4*)(bp + bj * HALF * 2 + lane_off) = w;
;                 }
;                 sq += __shfl_xor(sq, 16); sq += __shfl_xor(sq, 32);
;                 if (fq == 0) ssq[(size_t)(row0 + ai * HALF + m * 16) * 16 + u.pn * 4 + wc] = sq;
.LBB0_434:
	s_or_b64 exec, exec, s[24:25]
	v_pk_mul_f32 v[30:31], v[196:197], v[30:31]
	v_lshlrev_b32_e32 v38, 16, v134
	v_mov_b32_e32 v193, v192
	v_add_f32_e32 v30, v30, v38
	v_and_b32_e32 v38, 0xffff0000, v134
	v_pk_mul_f32 v[32:33], v[192:193], v[32:33]
	v_add_f32_e32 v31, v31, v38
	v_lshlrev_b32_e32 v38, 16, v135
	v_add_f32_e32 v32, v32, v38
	v_and_b32_e32 v38, 0xffff0000, v135
	v_pk_mul_f32 v[26:27], v[196:197], v[26:27]
	v_add_f32_e32 v33, v33, v38
	v_lshlrev_b32_e32 v38, 16, v136
	v_add_f32_e32 v38, v26, v38
	v_and_b32_e32 v26, 0xffff0000, v136
	v_pk_mul_f32 v[28:29], v[192:193], v[28:29]
	v_add_f32_e32 v39, v27, v26
	v_lshlrev_b32_e32 v26, 16, v137
	v_add_f32_e32 v40, v28, v26
	v_and_b32_e32 v26, 0xffff0000, v137
	v_add_f32_e32 v29, v29, v26
	v_mul_f32_e32 v26, v31, v31
	v_mul_f32_e32 v27, v33, v33
	v_fmac_f32_e32 v26, v30, v30
	v_fmac_f32_e32 v27, v32, v32
	v_add_f32_e32 v26, v26, v27
	v_mul_f32_e32 v27, v39, v39
	v_mul_f32_e32 v28, v29, v29
	v_fmac_f32_e32 v27, v38, v38
	v_fmac_f32_e32 v28, v40, v40
	v_add_f32_e32 v27, v27, v28
	v_add_f32_e32 v28, v26, v27
	v_cvt_pk_bf16_f32 v26, v30, v31
	v_pk_mul_f32 v[22:23], v[196:197], v[22:23]
	v_lshlrev_b32_e32 v30, 16, v130
	v_add_f32_e32 v22, v22, v30
	v_and_b32_e32 v30, 0xffff0000, v130
	v_pk_mul_f32 v[24:25], v[192:193], v[24:25]
	v_add_f32_e32 v23, v23, v30
	v_lshlrev_b32_e32 v30, 16, v131
	v_add_f32_e32 v24, v24, v30
	v_and_b32_e32 v30, 0xffff0000, v131
	v_pk_mul_f32 v[18:19], v[196:197], v[18:19]
	v_add_f32_e32 v25, v25, v30
	v_lshlrev_b32_e32 v30, 16, v132
	v_add_f32_e32 v30, v18, v30
	v_and_b32_e32 v18, 0xffff0000, v132
	v_pk_mul_f32 v[20:21], v[192:193], v[20:21]
	v_add_f32_e32 v31, v19, v18
	v_lshlrev_b32_e32 v18, 16, v133
	v_cvt_pk_bf16_f32 v27, v32, v33
	v_add_f32_e32 v32, v20, v18
	v_and_b32_e32 v18, 0xffff0000, v133
	v_add_f32_e32 v33, v21, v18
	v_mul_f32_e32 v18, v23, v23
	v_mul_f32_e32 v19, v25, v25
	v_fmac_f32_e32 v18, v22, v22
	v_fmac_f32_e32 v19, v24, v24
	v_add_f32_e32 v18, v18, v19
	v_mul_f32_e32 v19, v31, v31
	v_mul_f32_e32 v20, v33, v33
	v_fmac_f32_e32 v19, v30, v30
	v_fmac_f32_e32 v20, v32, v32
	v_add_f32_e32 v19, v19, v20
	v_add_f32_e32 v18, v18, v19
	v_add_f32_e32 v18, v28, v18
	v_mov_b32_e32 v19, v18
	s_nop 1
	v_permlane16_swap_b32_e32 v19, v18
	s_mov_b64 s[24:25], 0x50000
	s_waitcnt lgkmcnt(1)
	v_lshl_add_u64 v[34:35], v[206:207], 0, s[24:25]
	s_mov_b64 s[24:25], 0x50100
	v_lshl_add_u64 v[36:37], v[206:207], 0, s[24:25]
	s_waitcnt lgkmcnt(0)
	v_add_f32_e32 v18, v18, v19
	v_mov_b32_e32 v19, v18
	s_nop 1
	v_permlane32_swap_b32_e32 v19, v18
	v_cvt_pk_bf16_f32 v28, v38, v39
	v_cvt_pk_bf16_f32 v29, v40, v29
	global_store_dwordx4 v[34:35], v[26:29], off
	v_cvt_pk_bf16_f32 v20, v22, v23
	v_cvt_pk_bf16_f32 v21, v24, v25
	v_cvt_pk_bf16_f32 v22, v30, v31
	v_cvt_pk_bf16_f32 v23, v32, v33
	global_store_dwordx4 v[36:37], v[20:23], off
	s_and_saveexec_b64 s[24:25], s[4:5]
	s_cbranch_execz .LBB0_436
	s_waitcnt lgkmcnt(0)
	v_add_f32_e32 v20, v18, v19
	v_lshlrev_b64 v[18:19], 6, v[208:209]
	v_lshl_add_u64 v[18:19], s[12:13], 0, v[18:19]
	v_lshl_add_u64 v[18:19], s[44:45], 2, v[18:19]
	s_lshl_b32 s20, s55, 2
	v_lshl_add_u64 v[18:19], v[18:19], 0, s[20:21]
	v_add_co_u32_e32 v18, vcc, 0x2000, v18
	s_nop 1
	v_addc_co_u32_e32 v19, vcc, 0, v19, vcc
	global_store_dword v[18:19], v20, off offset:2048
.LBB0_436:
	s_or_b64 exec, exec, s[24:25]
	v_pk_mul_f32 v[14:15], v[196:197], v[14:15]
	v_lshlrev_b32_e32 v22, 16, v118
	v_add_f32_e32 v14, v14, v22
	v_and_b32_e32 v22, 0xffff0000, v118
	v_pk_mul_f32 v[16:17], v[192:193], v[16:17]
	v_add_f32_e32 v15, v15, v22
	v_lshlrev_b32_e32 v22, 16, v119
	v_add_f32_e32 v16, v16, v22
	v_and_b32_e32 v22, 0xffff0000, v119
	v_pk_mul_f32 v[10:11], v[196:197], v[10:11]
	v_add_f32_e32 v17, v17, v22
	v_lshlrev_b32_e32 v22, 16, v120
	v_add_f32_e32 v22, v10, v22
	v_and_b32_e32 v10, 0xffff0000, v120
	v_pk_mul_f32 v[12:13], v[192:193], v[12:13]
	v_add_f32_e32 v23, v11, v10
	v_lshlrev_b32_e32 v10, 16, v121
	v_add_f32_e32 v24, v12, v10
	v_and_b32_e32 v10, 0xffff0000, v121
	v_add_f32_e32 v13, v13, v10
	v_mul_f32_e32 v10, v15, v15
	v_mul_f32_e32 v11, v17, v17
	v_fmac_f32_e32 v10, v14, v14
	v_fmac_f32_e32 v11, v16, v16
	v_add_f32_e32 v10, v10, v11
	v_mul_f32_e32 v11, v23, v23
	v_mul_f32_e32 v12, v13, v13
	v_fmac_f32_e32 v11, v22, v22
	v_fmac_f32_e32 v12, v24, v24
	v_add_f32_e32 v11, v11, v12
	v_add_f32_e32 v12, v10, v11
	v_cvt_pk_bf16_f32 v10, v14, v15
	v_pk_mul_f32 v[6:7], v[196:197], v[6:7]
	v_lshlrev_b32_e32 v14, 16, v114
	v_add_f32_e32 v6, v6, v14
	v_and_b32_e32 v14, 0xffff0000, v114
	v_pk_mul_f32 v[8:9], v[192:193], v[8:9]
	v_add_f32_e32 v7, v7, v14
	v_lshlrev_b32_e32 v14, 16, v115
	v_add_f32_e32 v8, v8, v14
	v_and_b32_e32 v14, 0xffff0000, v115
	v_pk_mul_f32 v[2:3], v[196:197], v[2:3]
	v_add_f32_e32 v9, v9, v14
	v_lshlrev_b32_e32 v14, 16, v116
	v_add_f32_e32 v14, v2, v14
	v_and_b32_e32 v2, 0xffff0000, v116
	v_pk_mul_f32 v[4:5], v[192:193], v[4:5]
	v_add_f32_e32 v15, v3, v2
	v_lshlrev_b32_e32 v2, 16, v117
	v_cvt_pk_bf16_f32 v11, v16, v17
	v_add_f32_e32 v16, v4, v2
	v_and_b32_e32 v2, 0xffff0000, v117
	v_add_f32_e32 v17, v5, v2
	v_mul_f32_e32 v2, v7, v7
	v_mul_f32_e32 v3, v9, v9
	v_fmac_f32_e32 v2, v6, v6
	v_fmac_f32_e32 v3, v8, v8
	v_add_f32_e32 v2, v2, v3
	v_mul_f32_e32 v3, v15, v15
	v_mul_f32_e32 v4, v17, v17
	v_fmac_f32_e32 v3, v14, v14
	v_fmac_f32_e32 v4, v16, v16
	v_add_f32_e32 v3, v3, v4
	v_add_f32_e32 v2, v2, v3
	v_add_f32_e32 v2, v12, v2
	v_mov_b32_e32 v3, v2
	s_nop 1
	v_permlane16_swap_b32_e32 v3, v2
	s_mov_b64 s[24:25], 0x58000
	s_waitcnt lgkmcnt(1)
	v_lshl_add_u64 v[18:19], v[206:207], 0, s[24:25]
	s_mov_b64 s[24:25], 0x58100
	v_lshl_add_u64 v[20:21], v[206:207], 0, s[24:25]
	s_waitcnt lgkmcnt(0)
	v_add_f32_e32 v2, v2, v3
	v_mov_b32_e32 v3, v2
	s_nop 1
	v_permlane32_swap_b32_e32 v3, v2
	v_cvt_pk_bf16_f32 v12, v22, v23
	v_cvt_pk_bf16_f32 v13, v24, v13
	global_store_dwordx4 v[18:19], v[10:13], off
	v_cvt_pk_bf16_f32 v4, v6, v7
	v_cvt_pk_bf16_f32 v5, v8, v9
	v_cvt_pk_bf16_f32 v6, v14, v15
	v_cvt_pk_bf16_f32 v7, v16, v17
	global_store_dwordx4 v[20:21], v[4:7], off
	s_and_saveexec_b64 s[24:25], s[4:5]
	s_cbranch_execz .LBB0_438
	s_waitcnt lgkmcnt(0)
	v_add_f32_e32 v4, v2, v3
	v_lshlrev_b64 v[2:3], 6, v[208:209]
	v_lshl_add_u64 v[2:3], s[12:13], 0, v[2:3]
	v_lshl_add_u64 v[2:3], s[44:45], 2, v[2:3]
	s_lshl_b32 s20, s55, 2
	v_lshl_add_u64 v[2:3], v[2:3], 0, s[20:21]
	v_add_co_u32_e32 v2, vcc, 0x2000, v2
	s_nop 1
	v_addc_co_u32_e32 v3, vcc, 0, v3, vcc
	global_store_dword v[2:3], v4, off offset:3072
